# MLA-up item rebalance: the 16 trailing dilated items move from the workgroups that run 5 GEMM items to those that run 4
# baseline (speedup 1.0000x reference)
; DI void phase_mla_up(const KArgs& ka, int l, char* lds) {
;     ...
;   for (int q = jb; q < 144 + 192; q += nbx) {
;     if (q >= 144) {
;       __syncthreads();
;       const int q3 = q - 144, bh = xcd * 2 + q3 / 96, r3 = q3 % 96, pat = r3 >> 5, grp = r3 & 31;
;       attn_a_block(p, bh >> 2, bh & 3, pat, grp, lds);
;       continue;
;     }
;     const int mtl = q / 9, cc = q % 9;
.LBB0_274:
	v_readlane_b32 s81, v255, 62
	s_nop 0
	s_add_i32 s81, s81, s78
	s_cmpk_gt_u32 s81, 0x15f
	s_cbranch_scc1 .LBB0_310
.LBB0_275:
	v_writelane_b32 v255, s81, 62
	s_cmpk_lt_u32 s81, 0x140
	s_cbranch_scc1 .Lmu_ok
	s_sub_i32 s81, s81, 0x130
	s_and_b32 s81, s81, 31
	s_add_i32 s81, s81, 0x140
	s_cmpk_gt_u32 s81, 0x14f
	s_cbranch_scc1 .LBB0_274
